# block 0 parameter copy in phase 0: all 19 loads issued before one wait, then all stores (was 19 serialized load-store round trips)
# baseline (speedup 1.0000x reference)
; #define CPY(off, src, n) for (int i = tid; i < (n); i += 512) pw[(off) + i] = (src)[i]
; __global__ void __launch_bounds__(512) mk_fwd(Args a) {
;     ...
;     if (blockIdx.x == 0) {
;         float* pw = (float*)(a.ws + WS_PAR);
;     ...
;         CPY(P_CONV, a.in[7], 2304); CPY(P_DQN, a.in[8], 64); CPY(P_DKN, a.in[9], 64); CPY(P_LQ1, a.in[10], 64); CPY(P_LK1, a.in[11], 64); CPY(P_LQ2, a.in[12], 64); CPY(P_LK2, a.in[13], 64);
;         CPY(P_SUBN, a.in[14], 128); CPY(P_LQN, a.in[15], 128); CPY(P_LKN, a.in[16], 128); CPY(P_FIN, a.in[21], 2048); CPY(P_RB, a.in[22], 320);
;     ...
;     }
.Lnp_done:
.LBB0_97:
	s_cmp_lg_u32 s14, 0
	s_cbranch_scc1 .LBB0_109
	v_lshlrev_b32_e32 v0, 2, v154
	v_readlane_b32 s16, v234, 0
	v_readlane_b32 s17, v234, 1
	v_readlane_b32 s18, v234, 2
	v_readlane_b32 s19, v234, 3
	v_readlane_b32 s20, v234, 4
	v_readlane_b32 s21, v234, 5
	v_readlane_b32 s22, v234, 6
	v_readlane_b32 s23, v234, 7
	v_readlane_b32 s24, v234, 8
	v_readlane_b32 s25, v234, 9
	v_readlane_b32 s26, v234, 10
	v_readlane_b32 s27, v234, 11
	v_readlane_b32 s28, v234, 12
	v_readlane_b32 s29, v234, 13
	v_readlane_b32 s30, v234, 14
	v_readlane_b32 s31, v234, 15
	v_readlane_b32 s92, v234, 16
	v_readlane_b32 s93, v234, 17
	v_readlane_b32 s6, v234, 26
	v_readlane_b32 s7, v234, 27
	v_readlane_b32 s4, v234, 28
	v_readlane_b32 s5, v234, 29
	s_add_u32 s0, s72, 0xc0000
	s_addc_u32 s1, s73, 0
	v_add_u32_e32 v1, 0x1000, v0
	v_add_u32_e32 v2, 0x2000, v0
	v_add_u32_e32 v3, 0x3000, v0
	v_add_u32_e32 v4, 0x4000, v0
	v_add_u32_e32 v5, 0x5000, v0
	s_nop 4
	global_load_dword v12, v0, s[66:67]
	global_load_dword v13, v0, s[66:67] offset:2048
	global_load_dword v14, v1, s[66:67]
	global_load_dword v15, v1, s[66:67] offset:2048
	global_load_dword v16, v0, s[6:7]
	global_load_dword v17, v0, s[6:7] offset:2048
	global_load_dword v18, v1, s[6:7]
	global_load_dword v19, v1, s[6:7] offset:2048
	v_cmp_gt_u32_e32 vcc, 0x100, v154
	s_and_saveexec_b64 s[2:3], vcc
	global_load_dword v20, v2, s[66:67]
	s_mov_b64 exec, s[2:3]
	v_cmp_gt_u32_e32 vcc, 0x140, v154
	s_and_saveexec_b64 s[2:3], vcc
	global_load_dword v21, v0, s[4:5]
	s_mov_b64 exec, s[2:3]
	v_cmp_gt_u32_e32 vcc, 0x80, v154
	s_and_saveexec_b64 s[2:3], vcc
	global_load_dword v22, v0, s[28:29]
	global_load_dword v23, v0, s[30:31]
	global_load_dword v24, v0, s[92:93]
	s_mov_b64 exec, s[2:3]
	v_cmp_gt_u32_e32 vcc, 64, v154
	s_and_saveexec_b64 s[2:3], vcc
	global_load_dword v25, v0, s[16:17]
	global_load_dword v26, v0, s[18:19]
	global_load_dword v27, v0, s[20:21]
	global_load_dword v28, v0, s[22:23]
	global_load_dword v29, v0, s[24:25]
	global_load_dword v30, v0, s[26:27]
	s_mov_b64 exec, s[2:3]
	s_waitcnt vmcnt(0)
	global_store_dword v0, v12, s[0:1]
	global_store_dword v0, v13, s[0:1] offset:2048
	global_store_dword v1, v14, s[0:1]
	global_store_dword v1, v15, s[0:1] offset:2048
	global_store_dword v3, v16, s[0:1]
	global_store_dword v3, v17, s[0:1] offset:2048
	global_store_dword v4, v18, s[0:1]
	global_store_dword v4, v19, s[0:1] offset:2048
	v_cmp_gt_u32_e32 vcc, 0x100, v154
	s_and_saveexec_b64 s[2:3], vcc
	global_store_dword v2, v20, s[0:1]
	s_mov_b64 exec, s[2:3]
	v_cmp_gt_u32_e32 vcc, 0x140, v154
	s_and_saveexec_b64 s[2:3], vcc
	global_store_dword v5, v21, s[0:1]
	s_mov_b64 exec, s[2:3]
	v_cmp_gt_u32_e32 vcc, 0x80, v154
	s_and_saveexec_b64 s[2:3], vcc
	global_store_dword v2, v22, s[0:1] offset:2560
	global_store_dword v2, v23, s[0:1] offset:3072
	global_store_dword v2, v24, s[0:1] offset:3584
	s_mov_b64 exec, s[2:3]
	v_cmp_gt_u32_e32 vcc, 64, v154
	s_and_saveexec_b64 s[2:3], vcc
	global_store_dword v2, v25, s[0:1] offset:1024
	global_store_dword v2, v26, s[0:1] offset:1280
	global_store_dword v2, v27, s[0:1] offset:1536
	global_store_dword v2, v28, s[0:1] offset:1792
	global_store_dword v2, v29, s[0:1] offset:2048
	global_store_dword v2, v30, s[0:1] offset:2304
	s_mov_b64 exec, s[2:3]
	v_readlane_b32 s16, v234, 16
	v_readlane_b32 s17, v234, 17
	v_readlane_b32 s18, v234, 18
	v_readlane_b32 s19, v234, 19
	v_readlane_b32 s20, v234, 20
	v_readlane_b32 s21, v234, 21
	v_readlane_b32 s22, v234, 22
	v_readlane_b32 s23, v234, 23
	v_readlane_b32 s24, v234, 24
	v_readlane_b32 s25, v234, 25
	v_readlane_b32 s26, v234, 26
	v_readlane_b32 s27, v234, 27
	v_readlane_b32 s28, v234, 28
	v_readlane_b32 s29, v234, 29
	v_readlane_b32 s30, v234, 30
	v_readlane_b32 s31, v234, 31
